# phase-3 conversion tail: the 64 workgroups with the cheapest four units take the last 128 weight blocks (N1=496)
# speedup vs baseline: 1.0054x; 1.0054x over previous
.LBB0_330:
	s_abs_i32 s66, s84
	v_cvt_f32_u32_e32 v1, s66
	s_sub_i32 s0, 0, s66
	v_readlane_b32 s82, v254, 9
	v_rcp_iflag_f32_e32 v1, v1
	s_nop 0
	v_mul_f32_e32 v1, 0x4f7ffffe, v1
	v_cvt_u32_f32_e32 v1, v1
	s_nop 0
	v_readfirstlane_b32 s67, v1
	s_mul_i32 s0, s0, s67
	s_mul_hi_u32 s0, s67, s0
	s_add_i32 s67, s67, s0
	s_mul_hi_u32 s0, s67, 0x3c0
	s_mul_i32 s0, s0, s66
	s_sub_i32 s0, 0x3c0, s0
	s_sub_i32 s1, s0, s66
	s_cmp_ge_u32 s0, s66
	s_cselect_b32 s0, s1, s0
	s_sub_i32 s1, s0, s66
	s_cmp_ge_u32 s0, s66
	s_cselect_b32 s3, s1, s0
	s_cmp_lt_i32 s83, s3
	s_cbranch_scc1 .Ltail0_unitwg
	s_sub_i32 s2, s83, s3
	s_movk_i32 s98, 0x1f0
	s_cmp_eq_u32 s3, 0
	s_cselect_b32 s98, 0x270, s98
	s_sub_i32 s99, s84, s3
	s_branch .Ltail0_common
.Ltail0_unitwg:
	s_min_i32 s99, s3, 64
	s_add_i32 s2, s83, 0x1f0
	s_movk_i32 s98, 0x270
	s_cmp_lt_i32 s83, s99
	s_cselect_b32 s98, s98, 0
